# GEMM unit start: 128 accumulator registers zeroed by 8 zero-operand MFMAs instead of 128 v_mov (frees the shared VALU issue at unit transitions), on top of previous version
# baseline (speedup 1.0000x reference)
; template <class Epi, class Sched, bool ALIGN_EPI = false, bool SP2 = false>
; __device__ __forceinline__ void gemm_phase(PG8_LAS unsigned char* lds, const Gemm g, const Sched& S, const Epi& E) {
;     ...
;         const bool has_next = S.next(ui + 1, nxt);
;         const char* nA = has_next ? (const char*)g.A + (size_t)nxt.pm * tstepA : cA; const char* nB = has_next ? (const char*)g.Bt + (size_t)nxt.pn * tstepB : cB;
;     ...
; #pragma unroll
;         for (int a = 0; a < 2; ++a)
; #pragma unroll
;             for (int b = 0; b < 2; ++b)
; #pragma unroll
;                 for (int m = 0; m < 4; ++m)
; #pragma unroll
;                     for (int n = 0; n < 2; ++n) acc[a][b][m][n] = (f32x4){0.f, 0.f, 0.f, 0.f};
.LBB0_243:
	s_ashr_i32 s15, s14, 31
	s_lshl_b64 s[20:21], s[14:15], 19
	s_add_u32 s20, s60, s20
	s_addc_u32 s21, s61, s21
	s_and_b64 s[22:23], s[4:5], exec
	s_cselect_b32 s15, s21, s27
	s_cselect_b32 s62, s20, s26
	s_ashr_i32 s13, s12, 31
	s_lshl_b64 s[22:23], s[12:13], 19
	s_add_u32 s22, s34, s22
	s_addc_u32 s23, s35, s23
	s_and_b64 s[30:31], s[4:5], exec
	s_cselect_b32 s13, s23, s29
	s_cselect_b32 s63, s22, s28
	s_add_u32 s26, s26, 0x40080
	s_addc_u32 s27, s27, 0
	s_add_u32 s66, s28, 0x100
	s_addc_u32 s67, s29, 0
	s_mov_b32 s68, -2
	v_mov_b64_e32 v[228:229], 0
	v_mov_b64_e32 v[230:231], 0
	s_nop 1
	v_mfma_f32_32x32x16_bf16 v[0:15], v[228:231], v[228:231], 0
	v_mfma_f32_32x32x16_bf16 v[16:31], v[228:231], v[228:231], 0
	v_mfma_f32_32x32x16_bf16 v[32:47], v[228:231], v[228:231], 0
	v_mfma_f32_32x32x16_bf16 v[48:63], v[228:231], v[228:231], 0
	v_mfma_f32_32x32x16_bf16 v[64:79], v[228:231], v[228:231], 0
	v_mfma_f32_32x32x16_bf16 v[80:95], v[228:231], v[228:231], 0
	v_mfma_f32_32x32x16_bf16 v[96:111], v[228:231], v[228:231], 0
	v_mfma_f32_32x32x16_bf16 v[112:127], v[228:231], v[228:231], 0
	s_nop 0

; template <class Epi, class Sched, bool ALIGN_EPI = false, bool SP2 = false>
; __device__ __forceinline__ void gemm_phase(PG8_LAS unsigned char* lds, const Gemm g, const Sched& S, const Epi& E) {
;     ...
;         for (int t = 0; t < nt; t += 2) {
;             const bool last = (t == nt - 2);
;             const char* a1 = cA + (size_t)(t + 1) * kstep;
;             const char* a2 = last ? nA : cA + (size_t)(t + 2) * kstep; const char* b2 = last ? nB : cB + (size_t)(t + 2) * kstep;
;             const char* a3 = a2 + kstep; const char* b3 = b2 + kstep;
;     ...
; #pragma unroll
;         for (int a = 0; a < 2; ++a)
; #pragma unroll
;             for (int b = 0; b < 2; ++b)
; #pragma unroll
;                 for (int m = 0; m < 4; ++m)
; #pragma unroll
;                     for (int n = 0; n < 2; ++n) acc[a][b][m][n] = (f32x4){0.f, 0.f, 0.f, 0.f};
.LBB0_317:
	s_add_u32 s70, s28, 0x100
	s_addc_u32 s71, s29, 0
	s_mov_b32 s72, -2
	s_waitcnt lgkmcnt(0)
	v_mov_b64_e32 v[228:229], 0
	v_mov_b64_e32 v[230:231], 0
	s_nop 1
	v_mfma_f32_32x32x16_bf16 v[0:15], v[228:231], v[228:231], 0
	v_mfma_f32_32x32x16_bf16 v[16:31], v[228:231], v[228:231], 0
	v_mfma_f32_32x32x16_bf16 v[32:47], v[228:231], v[228:231], 0
	v_mfma_f32_32x32x16_bf16 v[48:63], v[228:231], v[228:231], 0
	v_mfma_f32_32x32x16_bf16 v[64:79], v[228:231], v[228:231], 0
	v_mfma_f32_32x32x16_bf16 v[80:95], v[228:231], v[228:231], 0
	v_mfma_f32_32x32x16_bf16 v[96:111], v[228:231], v[228:231], 0
	v_mfma_f32_32x32x16_bf16 v[112:127], v[228:231], v[228:231], 0
	s_nop 0

; template <class Epi, class Sched, bool ALIGN_EPI = false, bool SP2 = false>
; __device__ __forceinline__ void gemm_phase(PG8_LAS unsigned char* lds, const Gemm g, const Sched& S, const Epi& E) {
;     ...
;         for (int t = 0; t < nt; t += 2) {
;             const bool last = (t == nt - 2);
;             const char* a1 = cA + (size_t)(t + 1) * kstep;
;             const char* a2 = last ? nA : cA + (size_t)(t + 2) * kstep; const char* b2 = last ? nB : cB + (size_t)(t + 2) * kstep;
;             const char* a3 = a2 + kstep; const char* b3 = b2 + kstep;
;     ...
; #pragma unroll
;         for (int a = 0; a < 2; ++a)
; #pragma unroll
;             for (int b = 0; b < 2; ++b)
; #pragma unroll
;                 for (int m = 0; m < 4; ++m)
; #pragma unroll
;                     for (int n = 0; n < 2; ++n) acc[a][b][m][n] = (f32x4){0.f, 0.f, 0.f, 0.f};
.LBB0_523:
	s_add_u32 s74, s30, 0x100
	s_addc_u32 s75, s31, 0
	s_mov_b32 s76, -2
	v_mov_b64_e32 v[228:229], 0
	v_mov_b64_e32 v[230:231], 0
	s_nop 1
	v_mfma_f32_32x32x16_bf16 v[0:15], v[228:231], v[228:231], 0
	v_mfma_f32_32x32x16_bf16 v[16:31], v[228:231], v[228:231], 0
	v_mfma_f32_32x32x16_bf16 v[32:47], v[228:231], v[228:231], 0
	v_mfma_f32_32x32x16_bf16 v[48:63], v[228:231], v[228:231], 0
	v_mfma_f32_32x32x16_bf16 v[64:79], v[228:231], v[228:231], 0
	v_mfma_f32_32x32x16_bf16 v[80:95], v[228:231], v[228:231], 0
	v_mfma_f32_32x32x16_bf16 v[96:111], v[228:231], v[228:231], 0
	v_mfma_f32_32x32x16_bf16 v[112:127], v[228:231], v[228:231], 0
	s_nop 0

; template <class Epi, class Sched, bool ALIGN_EPI = false, bool SP2 = false>
; __device__ __forceinline__ void gemm_phase(PG8_LAS unsigned char* lds, const Gemm g, const Sched& S, const Epi& E) {
;     ...
;         const bool has_next = S.next(ui + 1, nxt);
;         const char* nA = has_next ? (const char*)g.A + (size_t)nxt.pm * tstepA : cA; const char* nB = has_next ? (const char*)g.Bt + (size_t)nxt.pn * tstepB : cB;
;     ...
; #pragma unroll
;         for (int a = 0; a < 2; ++a)
; #pragma unroll
;             for (int b = 0; b < 2; ++b)
; #pragma unroll
;                 for (int m = 0; m < 4; ++m)
; #pragma unroll
;                     for (int n = 0; n < 2; ++n) acc[a][b][m][n] = (f32x4){0.f, 0.f, 0.f, 0.f};
.LBB0_541:
	s_ashr_i32 s25, s24, 31
	s_lshl_b64 s[28:29], s[24:25], 17
	s_add_u32 s28, s66, s28
	s_addc_u32 s29, s67, s29
	s_and_b64 s[8:9], s[8:9], exec
	s_cselect_b32 s25, s29, s31
	s_cselect_b32 s89, s28, s30
	s_mov_b32 s38, 0
	s_mov_b64 s[8:9], -1
	s_mov_b64 s[36:37], 0
	v_mov_b64_e32 v[228:229], 0
	v_mov_b64_e32 v[230:231], 0
	s_nop 1
	v_mfma_f32_32x32x16_bf16 v[0:15], v[228:231], v[228:231], 0
	v_mfma_f32_32x32x16_bf16 v[16:31], v[228:231], v[228:231], 0
	v_mfma_f32_32x32x16_bf16 v[32:47], v[228:231], v[228:231], 0
	v_mfma_f32_32x32x16_bf16 v[48:63], v[228:231], v[228:231], 0
	v_mfma_f32_32x32x16_bf16 v[64:79], v[228:231], v[228:231], 0
	v_mfma_f32_32x32x16_bf16 v[80:95], v[228:231], v[228:231], 0
	v_mfma_f32_32x32x16_bf16 v[96:111], v[228:231], v[228:231], 0
	v_mfma_f32_32x32x16_bf16 v[112:127], v[228:231], v[228:231], 0
	s_nop 0

; template <class Epi, class Sched, bool ALIGN_EPI = false, bool SP2 = false>
; __device__ __forceinline__ void gemm_phase(PG8_LAS unsigned char* lds, const Gemm g, const Sched& S, const Epi& E) {
;     ...
;         const bool has_next = S.next(ui + 1, nxt);
;         const char* nA = has_next ? (const char*)g.A + (size_t)nxt.pm * tstepA : cA; const char* nB = has_next ? (const char*)g.Bt + (size_t)nxt.pn * tstepB : cB;
;     ...
; #pragma unroll
;         for (int a = 0; a < 2; ++a)
; #pragma unroll
;             for (int b = 0; b < 2; ++b)
; #pragma unroll
;                 for (int m = 0; m < 4; ++m)
; #pragma unroll
;                     for (int n = 0; n < 2; ++n) acc[a][b][m][n] = (f32x4){0.f, 0.f, 0.f, 0.f};
.LBB0_970:
	s_ashr_i32 s21, s20, 31
	s_lshl_b64 s[22:23], s[20:21], 19
	s_add_u32 s22, s62, s22
	s_addc_u32 s23, s63, s23
	s_and_b64 s[24:25], s[8:9], exec
	s_cselect_b32 s21, s23, s31
	s_cselect_b32 s27, s22, s30
	s_ashr_i32 s19, s18, 31
	s_lshl_b64 s[24:25], s[18:19], 19
	s_add_u32 s24, s3, s24
	s_addc_u32 s25, s38, s25
	s_and_b64 s[36:37], s[8:9], exec
	s_cselect_b32 s19, s25, s35
	s_cselect_b32 s68, s24, s34
	s_add_u32 s30, s30, 0x40080
	s_addc_u32 s31, s31, 0
	s_add_u32 s69, s34, 0x100
	s_addc_u32 s73, s35, 0
	s_mov_b32 s74, -2
	s_waitcnt lgkmcnt(0)
	s_waitcnt vmcnt(0)
	v_mov_b64_e32 v[228:229], 0
	v_mov_b64_e32 v[230:231], 0
	s_nop 1
	v_mfma_f32_32x32x16_bf16 v[0:15], v[228:231], v[228:231], 0
	v_mfma_f32_32x32x16_bf16 v[16:31], v[228:231], v[228:231], 0
	v_mfma_f32_32x32x16_bf16 v[32:47], v[228:231], v[228:231], 0
	v_mfma_f32_32x32x16_bf16 v[48:63], v[228:231], v[228:231], 0
	v_mfma_f32_32x32x16_bf16 v[64:79], v[228:231], v[228:231], 0
	v_mfma_f32_32x32x16_bf16 v[80:95], v[228:231], v[228:231], 0
	v_mfma_f32_32x32x16_bf16 v[96:111], v[228:231], v[228:231], 0
	v_mfma_f32_32x32x16_bf16 v[112:127], v[228:231], v[228:231], 0
	s_nop 0

; template <class Epi, class Sched, bool ALIGN_EPI = false, bool SP2 = false>
; __device__ __forceinline__ void gemm_phase(PG8_LAS unsigned char* lds, const Gemm g, const Sched& S, const Epi& E) {
;     ...
;         const bool has_next = S.next(ui + 1, nxt);
;         const char* nA = has_next ? (const char*)g.A + (size_t)nxt.pm * tstepA : cA; const char* nB = has_next ? (const char*)g.Bt + (size_t)nxt.pn * tstepB : cB;
;     ...
; #pragma unroll
;         for (int a = 0; a < 2; ++a)
; #pragma unroll
;             for (int b = 0; b < 2; ++b)
; #pragma unroll
;                 for (int m = 0; m < 4; ++m)
; #pragma unroll
;                     for (int n = 0; n < 2; ++n) acc[a][b][m][n] = (f32x4){0.f, 0.f, 0.f, 0.f};
.LBB0_1054:
	s_ashr_i32 s19, s18, 31
	s_lshl_b64 s[20:21], s[18:19], 19
	s_add_u32 s20, s60, s20
	s_addc_u32 s21, s61, s21
	s_and_b64 s[22:23], s[6:7], exec
	s_cselect_b32 s19, s21, s27
	s_cselect_b32 s49, s20, s26
	s_ashr_i32 s17, s16, 31
	s_lshl_b64 s[22:23], s[16:17], 19
	s_add_u32 s22, s3, s22
	s_addc_u32 s23, s34, s23
	s_and_b64 s[30:31], s[6:7], exec
	s_cselect_b32 s17, s23, s29
	s_cselect_b32 s66, s22, s28
	s_add_u32 s26, s26, 0x40080
	s_addc_u32 s27, s27, 0
	s_add_u32 s67, s28, 0x100
	s_addc_u32 s68, s29, 0
	s_mov_b32 s69, -2
	s_waitcnt vmcnt(0)
	v_mov_b64_e32 v[228:229], 0
	v_mov_b64_e32 v[230:231], 0
	s_nop 1
	v_mfma_f32_32x32x16_bf16 v[0:15], v[228:231], v[228:231], 0
	v_mfma_f32_32x32x16_bf16 v[16:31], v[228:231], v[228:231], 0
	v_mfma_f32_32x32x16_bf16 v[32:47], v[228:231], v[228:231], 0
	v_mfma_f32_32x32x16_bf16 v[48:63], v[228:231], v[228:231], 0
	v_mfma_f32_32x32x16_bf16 v[64:79], v[228:231], v[228:231], 0
	v_mfma_f32_32x32x16_bf16 v[80:95], v[228:231], v[228:231], 0
	v_mfma_f32_32x32x16_bf16 v[96:111], v[228:231], v[228:231], 0
	v_mfma_f32_32x32x16_bf16 v[112:127], v[228:231], v[228:231], 0
	s_nop 0

; template <class Epi, class Sched, bool ALIGN_EPI = false, bool SP2 = false>
; __device__ __forceinline__ void gemm_phase(PG8_LAS unsigned char* lds, const Gemm g, const Sched& S, const Epi& E) {
;     ...
;         for (int t = 0; t < nt; t += 2) {
;             const bool last = (t == nt - 2);
;             const char* a1 = cA + (size_t)(t + 1) * kstep;
;             const char* a2 = last ? nA : cA + (size_t)(t + 2) * kstep; const char* b2 = last ? nB : cB + (size_t)(t + 2) * kstep;
;             const char* a3 = a2 + kstep; const char* b3 = b2 + kstep;
;     ...
; #pragma unroll
;         for (int a = 0; a < 2; ++a)
; #pragma unroll
;             for (int b = 0; b < 2; ++b)
; #pragma unroll
;                 for (int m = 0; m < 4; ++m)
; #pragma unroll
;                     for (int n = 0; n < 2; ++n) acc[a][b][m][n] = (f32x4){0.f, 0.f, 0.f, 0.f};
.LBB0_1128:
	s_add_u32 s67, s24, 0x100
	s_addc_u32 s68, s25, 0
	s_mov_b32 s69, -2
	s_waitcnt lgkmcnt(0)
	s_waitcnt vmcnt(0)
	v_mov_b64_e32 v[228:229], 0
	v_mov_b64_e32 v[230:231], 0
	s_nop 1
	v_mfma_f32_32x32x16_bf16 v[0:15], v[228:231], v[228:231], 0
	v_mfma_f32_32x32x16_bf16 v[16:31], v[228:231], v[228:231], 0
	v_mfma_f32_32x32x16_bf16 v[32:47], v[228:231], v[228:231], 0
	v_mfma_f32_32x32x16_bf16 v[48:63], v[228:231], v[228:231], 0
	v_mfma_f32_32x32x16_bf16 v[64:79], v[228:231], v[228:231], 0
	v_mfma_f32_32x32x16_bf16 v[80:95], v[228:231], v[228:231], 0
	v_mfma_f32_32x32x16_bf16 v[96:111], v[228:231], v[228:231], 0
	v_mfma_f32_32x32x16_bf16 v[112:127], v[228:231], v[228:231], 0
	s_nop 0

; template <class Epi, class Sched, bool ALIGN_EPI = false, bool SP2 = false>
; __device__ __forceinline__ void gemm_phase(PG8_LAS unsigned char* lds, const Gemm g, const Sched& S, const Epi& E) {
;     ...
;         const bool has_next = S.next(ui + 1, nxt);
;         const char* nA = has_next ? (const char*)g.A + (size_t)nxt.pm * tstepA : cA; const char* nB = has_next ? (const char*)g.Bt + (size_t)nxt.pn * tstepB : cB;
;     ...
; #pragma unroll
;         for (int a = 0; a < 2; ++a)
; #pragma unroll
;             for (int b = 0; b < 2; ++b)
; #pragma unroll
;                 for (int m = 0; m < 4; ++m)
; #pragma unroll
;                     for (int n = 0; n < 2; ++n) acc[a][b][m][n] = (f32x4){0.f, 0.f, 0.f, 0.f};
.LBB0_1160:
	s_ashr_i32 s25, s24, 31
	s_lshl_b64 s[26:27], s[24:25], 17
	s_add_u32 s26, s68, s26
	s_addc_u32 s27, s69, s27
	s_and_b64 s[28:29], s[6:7], exec
	s_cselect_b32 s25, s27, s37
	s_cselect_b32 s89, s26, s36
	s_ashr_i32 s23, s22, 31
	s_lshl_b64 s[28:29], s[22:23], 17
	s_add_u32 s28, s3, s28
	s_addc_u32 s29, s66, s29
	s_and_b64 s[38:39], s[6:7], exec
	s_cselect_b32 s23, s29, s35
	s_cselect_b32 s90, s28, s34
	s_mov_b32 s42, 0
	s_mov_b64 s[38:39], -1
	s_mov_b64 s[40:41], 0
	v_mov_b64_e32 v[228:229], 0
	v_mov_b64_e32 v[230:231], 0
	s_nop 1
	v_mfma_f32_32x32x16_bf16 v[0:15], v[228:231], v[228:231], 0
	v_mfma_f32_32x32x16_bf16 v[16:31], v[228:231], v[228:231], 0
	v_mfma_f32_32x32x16_bf16 v[32:47], v[228:231], v[228:231], 0
	v_mfma_f32_32x32x16_bf16 v[48:63], v[228:231], v[228:231], 0
	v_mfma_f32_32x32x16_bf16 v[64:79], v[228:231], v[228:231], 0
	v_mfma_f32_32x32x16_bf16 v[80:95], v[228:231], v[228:231], 0
	v_mfma_f32_32x32x16_bf16 v[96:111], v[228:231], v[228:231], 0
	v_mfma_f32_32x32x16_bf16 v[112:127], v[228:231], v[228:231], 0
	s_nop 0
